# attention head loop: QK and PV LDS fragment reads software-pipelined two groups ahead
# speedup vs baseline: 1.0120x; 1.0039x over previous
; __device__ __forceinline__ u32x4 pack8(f32x4 a, f32x4 b) { u32x4 w; w.x = cvt_pk_bf16(a[0], a[1]); w.y = cvt_pk_bf16(a[2], a[3]); w.z = cvt_pk_bf16(b[0], b[1]); w.w = cvt_pk_bf16(b[2], b[3]); return w; }
; __device__ __forceinline__ void unpack8(u32x4 w, f32x4& a, f32x4& b) { a = (f32x4){bf_lo(w.x), bf_hi(w.x), bf_lo(w.y), bf_hi(w.y)}; b = (f32x4){bf_lo(w.z), bf_hi(w.z), bf_lo(w.w), bf_hi(w.w)}; }
; #define LAS __attribute__((address_space(3)))
; __device__ __forceinline__ void attn_unit(LAS unsigned char* lds, const bf16_t* PROJ, bf16_t* YCAT, const float* qg, const float* kg, const float* sinks, int unit, int tid, int wave, int lane) {
;     ...
;         u32x4 w[4]; float ss = 0.f;
; #pragma unroll
;         for (int ks = 0; ks < 4; ++ks) w[ks] = qnx[ks];
;         {
;             const int hn = (hq + 1 < 4 * kvh + 4) ? hq + 1 : hq;
;             const bf16_t* qpn = PROJ + (size_t)(t0 + qrow) * INW + hn * 128 + 8 * fq;
; #pragma unroll
;             for (int ks = 0; ks < 4; ++ks) qnx[ks] = *(const u32x4*)(qpn + 32 * ks);
;         }
; #pragma unroll
;         for (int ks = 0; ks < 4; ++ks) { f32x4 v0, v1; pg8::unpack8(w[ks], v0, v1);
;             ss += (v0[0] * v0[0] + v0[1] * v0[1]) + (v0[2] * v0[2] + v0[3] * v0[3]) + (v1[0] * v1[0] + v1[1] * v1[1]) + (v1[2] * v1[2] + v1[3] * v1[3]); }
;         ss += __shfl_xor(ss, 16); ss += __shfl_xor(ss, 32);
;         const float rs = rsqrtf(ss * (1.f / 128.f) + EPS) * 0.08838834764831845f;
; #pragma unroll
;         for (int ks = 0; ks < 4; ++ks) { f32x4 v0, v1; pg8::unpack8(w[ks], v0, v1);
;             const f32x4 g0 = *(const f32x4*)(qg + 32 * ks + 8 * fq), g1 = *(const f32x4*)(qg + 32 * ks + 8 * fq + 4);
;             qf[ks] = as_bf8(pg8::pack8(v0 * rs * g0, v1 * rs * g1)); }
;     }
;     ...
;     for (int rel = 0; rel < 10; ++rel) {
;         s[rel] = (f32x4){0.f, 0.f, 0.f, 0.f};
; #pragma unroll
;         for (int ks = 0; ks < 4; ++ks) {
;             const bf16x8 kf = *(const LAS bf16x8*)(Ks + (16 * (wp + rel) + fr) * 136 + 32 * ks + 8 * fq);
;             s[rel] = __builtin_amdgcn_mfma_f32_16x16x32_bf16(kf, qf[ks], s[rel], 0, 0, 0);
.LBB0_172:
	s_nop 0
	v_and_b32_e32 v51, 0xffff0000, v31
	v_and_b32_e32 v55, 0xffff0000, v30
	v_and_b32_e32 v54, 0xffff0000, v32
	v_lshlrev_b32_e32 v50, 16, v31
	v_mul_f32_e32 v0, v51, v51
	v_lshlrev_b32_e32 v53, 16, v30
	v_lshlrev_b32_e32 v52, 16, v32
	v_pk_mul_f32 v[30:31], v[54:55], v[54:55]
	v_pk_fma_f32 v[34:35], v[50:51], v[50:51], v[0:1] op_sel_hi:[1,1,0]
	v_pk_fma_f32 v[30:31], v[52:53], v[52:53], v[30:31]
	s_nop 0
	v_and_b32_e32 v39, 0xffff0000, v27
	v_pk_add_f32 v[34:35], v[30:31], v[34:35] op_sel:[1,0] op_sel_hi:[0,1]
	v_and_b32_e32 v38, 0xffff0000, v26
	v_pk_add_f32 v[42:43], v[30:31], v[34:35]
	v_lshlrev_b32_e32 v37, 16, v27
	v_lshlrev_b32_e32 v36, 16, v26
	v_pk_mul_f32 v[26:27], v[38:39], v[38:39]
	v_and_b32_e32 v35, 0xffff0000, v29
	v_and_b32_e32 v34, 0xffff0000, v28
	v_lshlrev_b32_e32 v56, 16, v33
	v_and_b32_e32 v57, 0xffff0000, v33
	v_pk_fma_f32 v[26:27], v[36:37], v[36:37], v[26:27]
	v_lshlrev_b32_e32 v33, 16, v29
	v_lshlrev_b32_e32 v32, 16, v28
	v_pk_mul_f32 v[28:29], v[34:35], v[34:35]
	s_nop 0
	v_and_b32_e32 v41, 0xffff0000, v18
	v_pk_add_f32 v[26:27], v[26:27], v[26:27] op_sel:[0,1] op_sel_hi:[1,0]
	v_pk_fma_f32 v[44:45], v[32:33], v[32:33], v[28:29]
	v_lshlrev_b32_e32 v40, 16, v18
	v_and_b32_e32 v59, 0xffff0000, v19
	v_mul_f32_e32 v0, v41, v41
	v_pk_add_f32 v[46:47], v[44:45], v[26:27]
	v_lshlrev_b32_e32 v58, 16, v19
	s_nop 0
	v_lshlrev_b32_e32 v26, 16, v23
	v_and_b32_e32 v27, 0xffff0000, v23
	v_pk_fma_f32 v[60:61], v[40:41], v[40:41], v[0:1] op_sel_hi:[1,1,0]
	v_mul_f32_e32 v0, v59, v59
	v_mul_f32_e32 v18, v26, v26
	v_mul_f32_e32 v64, v27, v27
	v_and_b32_e32 v31, 0xffff0000, v22
	v_and_b32_e32 v30, 0xffff0000, v20
	v_pk_mov_b32 v[48:49], v[20:21], v[24:25] op_sel:[1,0]
	v_pk_fma_f32 v[62:63], v[58:59], v[58:59], v[0:1] op_sel_hi:[1,1,0]
	v_lshlrev_b32_e32 v23, 16, v25
	v_and_b32_e32 v19, 0xffff0000, v25
	v_lshlrev_b32_e32 v29, 16, v22
	v_lshlrev_b32_e32 v28, 16, v20
	v_lshlrev_b32_e32 v25, 16, v24
	v_lshlrev_b32_e32 v24, 16, v21
	v_and_b32_e32 v21, 0xffff0000, v49
	v_and_b32_e32 v20, 0xffff0000, v48
	v_pk_mul_f32 v[48:49], v[30:31], v[30:31]
	v_mov_b32_e32 v61, v18
	v_mov_b32_e32 v63, v64
	v_pk_fma_f32 v[48:49], v[28:29], v[28:29], v[48:49]
	v_pk_add_f32 v[60:61], v[60:61], v[62:63]
	v_mul_f32_e32 v0, v57, v57
	v_pk_add_f32 v[48:49], v[48:49], v[60:61]
	v_pk_mul_f32 v[60:61], v[20:21], v[20:21]
	s_add_i32 s87, s78, 1
	v_pk_fma_f32 v[60:61], v[24:25], v[24:25], v[60:61]
	v_mov_b32_e32 v62, v42
	v_pk_add_f32 v[48:49], v[60:61], v[48:49]
	v_pk_fma_f32 v[60:61], v[56:57], v[56:57], v[0:1] op_sel_hi:[1,1,0]
	v_mov_b32_e32 v63, v23
	v_mov_b32_e32 v22, v60
	s_cmp_lt_u32 s87, s86
	v_mul_f32_e32 v65, v19, v19
	v_pk_add_f32 v[42:43], v[60:61], v[42:43]
	v_pk_mul_f32 v[60:61], v[22:23], v[62:63]
	v_pk_add_f32 v[44:45], v[44:45], v[46:47] op_sel:[1,0] op_sel_hi:[0,1]
	s_cselect_b32 s78, s87, s78
	v_mov_b32_e32 v43, v61
	v_mov_b32_e32 v45, v65
	s_lshl_b32 s78, s78, 7
	v_pk_add_f32 v[42:43], v[42:43], v[44:45]
	v_lshl_add_u64 v[14:15], s[78:79], 1, v[92:93]
	v_pk_add_f32 v[42:43], v[42:43], v[48:49]
	global_load_dwordx4 v[2:5], v[14:15], off
	global_load_dwordx4 v[6:9], v[14:15], off offset:64
	global_load_dwordx4 v[10:13], v[14:15], off offset:128
	s_nop 0
	global_load_dwordx4 v[14:17], v[14:15], off offset:192
	v_add_f32_e32 v0, v42, v43
	s_nop 0
	s_nop 0
	ds_bpermute_b32 v18, v100, v0
	v_mov_b32_e32 v60, v53
	v_mov_b32_e32 v61, v55
	v_mov_b32_e32 v53, v54
	v_mov_b32_e32 v54, v36
	s_waitcnt lgkmcnt(0)
	v_add_f32_e32 v0, v0, v18
	ds_bpermute_b32 v18, v101, v0
	v_mov_b32_e32 v55, v38
	v_mov_b32_e32 v38, v37
	s_mov_b32 s78, 0x42fc0000
	s_waitcnt lgkmcnt(0)
	v_add_f32_e32 v0, v0, v18
	v_fmamk_f32 v0, v0, 0x3c000000, v197
	v_cmp_gt_f32_e32 vcc, s76, v0
	v_mul_f32_e32 v18, 0x4b800000, v0
	s_nop 0
	v_cndmask_b32_e32 v0, v0, v18, vcc
	v_rsq_f32_e32 v0, v0
	s_nop 0
	v_mul_f32_e32 v18, 0x45800000, v0
	v_cndmask_b32_e32 v0, v0, v18, vcc
	v_mul_f32_e32 v0, 0x3db504f3, v0
	v_pk_mul_f32 v[50:51], v[0:1], v[50:51] op_sel_hi:[0,1]
	v_pk_mul_f32 v[60:61], v[0:1], v[60:61] op_sel_hi:[0,1]
	v_pk_mul_f32 v[54:55], v[0:1], v[54:55] op_sel_hi:[0,1]
	v_pk_mul_f32 v[36:37], v[0:1], v[38:39] op_sel_hi:[0,1]
	v_pk_mul_f32 v[40:41], v[0:1], v[40:41] op_sel_hi:[0,1]
	v_mov_b32_e32 v18, v23
	v_pk_mul_f32 v[18:19], v[0:1], v[18:19] op_sel_hi:[0,1]
	v_pk_mul_f32 v[26:27], v[0:1], v[26:27] op_sel_hi:[0,1]
	s_nop 0
	v_pk_mul_f32 v[48:49], v[210:211], v[50:51]
	v_pk_mul_f32 v[50:51], v[0:1], v[52:53] op_sel_hi:[0,1]
	v_pk_mul_f32 v[52:53], v[0:1], v[56:57] op_sel_hi:[0,1]
	v_pk_mul_f32 v[46:47], v[208:209], v[60:61]
	v_pk_mul_f32 v[52:53], v[214:215], v[52:53]
	v_pk_mul_f32 v[44:45], v[212:213], v[50:51]
	v_cvt_pk_bf16_f32 v42, v46, v47
	v_cvt_pk_bf16_f32 v43, v48, v49
	s_nop 0
	v_cvt_pk_bf16_f32 v44, v44, v45
	v_cvt_pk_bf16_f32 v45, v52, v53
	s_nop 0
	s_nop 0
	s_nop 0
	v_pk_mul_f32 v[38:39], v[216:217], v[54:55]
	v_mov_b32_e32 v50, v32
	v_mov_b32_e32 v51, v34
	v_mov_b32_e32 v34, v33
	v_pk_mul_f32 v[50:51], v[0:1], v[50:51] op_sel_hi:[0,1]
	v_pk_mul_f32 v[32:33], v[0:1], v[34:35] op_sel_hi:[0,1]
	v_pk_mul_f32 v[36:37], v[218:219], v[36:37]
	v_pk_mul_f32 v[32:33], v[222:223], v[32:33]
	v_pk_mul_f32 v[34:35], v[220:221], v[50:51]
	v_cvt_pk_bf16_f32 v62, v38, v39
	v_cvt_pk_bf16_f32 v63, v36, v37
	v_pk_mul_f32 v[46:47], v[0:1], v[58:59] op_sel_hi:[0,1]
	v_cvt_pk_bf16_f32 v64, v34, v35
	v_cvt_pk_bf16_f32 v65, v32, v33
	s_nop 0
	s_nop 0
	s_nop 0
	v_pk_mul_f32 v[38:39], v[226:227], v[46:47]
	v_pk_mul_f32 v[36:37], v[224:225], v[40:41]
	v_mov_b32_e32 v40, v28
	v_mov_b32_e32 v41, v30
	v_mov_b32_e32 v46, v24
	v_mov_b32_e32 v47, v20
	v_pk_mul_f32 v[40:41], v[0:1], v[40:41] op_sel_hi:[0,1]
	v_pk_mul_f32 v[46:47], v[0:1], v[46:47] op_sel_hi:[0,1]
	v_pk_mul_f32 v[34:35], v[230:231], v[46:47]
	v_pk_mul_f32 v[32:33], v[228:229], v[40:41]
	v_cvt_pk_bf16_f32 v58, v36, v37
	v_cvt_pk_bf16_f32 v59, v38, v39
	v_mov_b32_e32 v20, v25
	v_cvt_pk_bf16_f32 v60, v32, v33
	v_cvt_pk_bf16_f32 v61, v34, v35
	s_nop 0
	s_nop 0
	v_mov_b32_e32 v30, v29
	v_pk_mul_f32 v[20:21], v[0:1], v[20:21] op_sel_hi:[0,1]
	v_pk_mul_f32 v[28:29], v[0:1], v[30:31] op_sel_hi:[0,1]
	v_cvt_f32_u32_e32 v0, s87
	v_cmp_lt_f32_e32 vcc, s78, v0
	s_nop 0
	v_pk_mul_f32 v[18:19], v[18:19], v[238:239]
	v_pk_mul_f32 v[20:21], v[20:21], v[236:237]
	s_nop 0
	v_pk_mul_f32 v[26:27], v[26:27], v[234:235]
	v_pk_mul_f32 v[28:29], v[28:29], v[232:233]
	s_nop 0
	v_cvt_pk_bf16_f32 v66, v28, v29
	v_cvt_pk_bf16_f32 v67, v26, v27
	v_cvt_pk_bf16_f32 v68, v20, v21
	v_cvt_pk_bf16_f32 v69, v18, v19
	ds_read_b128 v[176:179], v146
	ds_read_b128 v[180:183], v146 offset:64
	ds_read_b128 v[184:187], v146 offset:128
	ds_read_b128 v[188:191], v146 offset:192
	ds_read_b128 v[240:243], v147
	ds_read_b128 v[244:247], v147 offset:64
	ds_read_b128 v[248:251], v147 offset:128
	ds_read_b128 v[170:173], v147 offset:192
	s_waitcnt lgkmcnt(4)
; #define LAS __attribute__((address_space(3)))
; __device__ __forceinline__ void attn_unit(LAS unsigned char* lds, const bf16_t* PROJ, bf16_t* YCAT, const float* qg, const float* kg, const float* sinks, int unit, int tid, int wave, int lane) {
;     ...
;     for (int rel = 0; rel < 10; ++rel) {
;         s[rel] = (f32x4){0.f, 0.f, 0.f, 0.f};
; #pragma unroll
;         for (int ks = 0; ks < 4; ++ks) {
;             const bf16x8 kf = *(const LAS bf16x8*)(Ks + (16 * (wp + rel) + fr) * 136 + 32 * ks + 8 * fq);
;             s[rel] = __builtin_amdgcn_mfma_f32_16x16x32_bf16(kf, qf[ks], s[rel], 0, 0, 0);
;         }
;     }
;     const float slope = exp2f(-(float)(hq + 1)), sink = sinks[hq];
;     const int qidx = 128 + qrow;
;     float mx = -INFINITY;
; #pragma unroll
;     for (int rel = 0; rel < 10; ++rel)
; #pragma unroll
;         for (int i = 0; i < 4; ++i) {
;             const int kidx = 16 * (wp + rel) + 4 * fq + i, dist = qidx - kidx;
;             const bool valid = (dist >= 0) && (dist < 128) && (blk > 0 || kidx >= 128);
;             const float val = valid ? s[rel][i] - slope * (float)dist : -INFINITY;
;             s[rel][i] = val; mx = fmaxf(mx, val);
	v_mfma_f32_16x16x32_bf16 v[54:57], v[176:179], v[42:45], 0
	v_mfma_f32_16x16x32_bf16 v[54:57], v[180:183], v[62:65], v[54:57]
	v_mfma_f32_16x16x32_bf16 v[54:57], v[184:187], v[58:61], v[54:57]
	v_mfma_f32_16x16x32_bf16 v[54:57], v[188:191], v[66:69], v[54:57]
	ds_read_b128 v[176:179], v148
	ds_read_b128 v[180:183], v148 offset:64
	ds_read_b128 v[184:187], v148 offset:128
	ds_read_b128 v[188:191], v148 offset:192
	s_waitcnt lgkmcnt(4)
	v_mfma_f32_16x16x32_bf16 v[50:53], v[240:243], v[42:45], 0
	v_mfma_f32_16x16x32_bf16 v[50:53], v[244:247], v[62:65], v[50:53]
	v_mfma_f32_16x16x32_bf16 v[50:53], v[248:251], v[58:61], v[50:53]
	v_mfma_f32_16x16x32_bf16 v[50:53], v[170:173], v[66:69], v[50:53]
	ds_read_b128 v[240:243], v149
	ds_read_b128 v[244:247], v149 offset:64
	ds_read_b128 v[248:251], v149 offset:128
	ds_read_b128 v[170:173], v149 offset:192
	s_waitcnt lgkmcnt(4)
	v_mfma_f32_16x16x32_bf16 v[46:49], v[176:179], v[42:45], 0
	v_mfma_f32_16x16x32_bf16 v[46:49], v[180:183], v[62:65], v[46:49]
	v_mfma_f32_16x16x32_bf16 v[46:49], v[184:187], v[58:61], v[46:49]
	v_mfma_f32_16x16x32_bf16 v[46:49], v[188:191], v[66:69], v[46:49]
	ds_read_b128 v[176:179], v150
	ds_read_b128 v[180:183], v150 offset:64
	ds_read_b128 v[184:187], v150 offset:128
	ds_read_b128 v[188:191], v150 offset:192
	s_waitcnt lgkmcnt(4)
	v_mfma_f32_16x16x32_bf16 v[38:41], v[240:243], v[42:45], 0
	v_mfma_f32_16x16x32_bf16 v[38:41], v[244:247], v[62:65], v[38:41]
	v_mfma_f32_16x16x32_bf16 v[38:41], v[248:251], v[58:61], v[38:41]
	v_mfma_f32_16x16x32_bf16 v[38:41], v[170:173], v[66:69], v[38:41]
	ds_read_b128 v[240:243], v151
	ds_read_b128 v[244:247], v151 offset:64
	ds_read_b128 v[248:251], v151 offset:128
	ds_read_b128 v[170:173], v151 offset:192
	s_waitcnt lgkmcnt(4)
	v_mfma_f32_16x16x32_bf16 v[34:37], v[176:179], v[42:45], 0
	v_mfma_f32_16x16x32_bf16 v[34:37], v[180:183], v[62:65], v[34:37]
	v_mfma_f32_16x16x32_bf16 v[34:37], v[184:187], v[58:61], v[34:37]
	v_mfma_f32_16x16x32_bf16 v[34:37], v[188:191], v[66:69], v[34:37]
	ds_read_b128 v[176:179], v152
	ds_read_b128 v[180:183], v152 offset:64
	ds_read_b128 v[184:187], v152 offset:128
	ds_read_b128 v[188:191], v152 offset:192
	s_waitcnt lgkmcnt(4)
	v_mfma_f32_16x16x32_bf16 v[30:33], v[240:243], v[42:45], 0
	v_mfma_f32_16x16x32_bf16 v[30:33], v[244:247], v[62:65], v[30:33]
	v_mfma_f32_16x16x32_bf16 v[30:33], v[248:251], v[58:61], v[30:33]
	v_mfma_f32_16x16x32_bf16 v[30:33], v[170:173], v[66:69], v[30:33]
	ds_read_b128 v[240:243], v153
	ds_read_b128 v[244:247], v153 offset:64
	ds_read_b128 v[248:251], v153 offset:128
	ds_read_b128 v[170:173], v153 offset:192
	s_waitcnt lgkmcnt(4)
	v_mfma_f32_16x16x32_bf16 v[26:29], v[176:179], v[42:45], 0
	v_mfma_f32_16x16x32_bf16 v[26:29], v[180:183], v[62:65], v[26:29]
	v_mfma_f32_16x16x32_bf16 v[26:29], v[184:187], v[58:61], v[26:29]
	v_mfma_f32_16x16x32_bf16 v[26:29], v[188:191], v[66:69], v[26:29]
	ds_read_b128 v[176:179], v154
	ds_read_b128 v[180:183], v154 offset:64
	ds_read_b128 v[184:187], v154 offset:128
	ds_read_b128 v[188:191], v154 offset:192
	s_waitcnt lgkmcnt(4)
	v_mfma_f32_16x16x32_bf16 v[22:25], v[240:243], v[42:45], 0
	v_mfma_f32_16x16x32_bf16 v[22:25], v[244:247], v[62:65], v[22:25]
	v_mfma_f32_16x16x32_bf16 v[22:25], v[248:251], v[58:61], v[22:25]
	v_mfma_f32_16x16x32_bf16 v[22:25], v[170:173], v[66:69], v[22:25]
	ds_read_b128 v[240:243], v155
	ds_read_b128 v[244:247], v155 offset:64
	ds_read_b128 v[248:251], v155 offset:128
	ds_read_b128 v[170:173], v155 offset:192
	s_waitcnt lgkmcnt(4)
	v_mfma_f32_16x16x32_bf16 v[18:21], v[176:179], v[42:45], 0
	v_mfma_f32_16x16x32_bf16 v[18:21], v[180:183], v[62:65], v[18:21]
	v_mfma_f32_16x16x32_bf16 v[18:21], v[184:187], v[58:61], v[18:21]
	v_mfma_f32_16x16x32_bf16 v[18:21], v[188:191], v[66:69], v[18:21]
	s_waitcnt lgkmcnt(0)
	v_mfma_f32_16x16x32_bf16 v[42:45], v[240:243], v[42:45], 0
	v_mfma_f32_16x16x32_bf16 v[42:45], v[244:247], v[62:65], v[42:45]
	v_mfma_f32_16x16x32_bf16 v[42:45], v[248:251], v[58:61], v[42:45]
	v_mfma_f32_16x16x32_bf16 v[42:45], v[170:173], v[66:69], v[42:45]
	v_cndmask_b32_e32 v58, 0, v203, vcc
	v_sub_f32_e32 v0, v58, v0
	v_exp_f32_e32 v0, v0
	s_and_b64 vcc, vcc, exec
	s_cselect_b32 s78, 0xffffffc0, 0
	v_lshl_add_u64 v[60:61], v[88:89], 0, s[2:3]
	v_ldexp_f32 v58, v0, s78
	global_load_dword v0, v[60:61], off
	v_fma_f32 v54, -v58, v77, v54
	v_cndmask_b32_e64 v59, v204, v54, s[8:9]
	v_fma_f32 v54, -v58, v102, v55
	v_fma_f32 v56, -v58, v103, v56
	v_cndmask_b32_e64 v54, v204, v54, s[10:11]
	s_mov_b32 s78, 0xff800000
	v_cndmask_b32_e64 v174, v204, v56, s[12:13]
	v_fma_f32 v56, -v58, v104, v57
	v_fma_f32 v50, -v58, v105, v50
	v_max3_f32 v55, v59, s78, v54
	v_cndmask_b32_e64 v173, v204, v56, s[14:15]
	v_cndmask_b32_e64 v172, v204, v50, s[16:17]
	v_fma_f32 v50, -v58, v106, v51
	v_fma_f32 v51, -v58, v107, v52
	v_max3_f32 v55, v55, v174, v173
	v_cndmask_b32_e64 v171, v204, v50, s[18:19]
	v_cndmask_b32_e64 v170, v204, v51, s[20:21]
	v_fma_f32 v51, -v58, v108, v53
	v_fma_f32 v46, -v58, v109, v46
	v_max3_f32 v50, v55, v172, v171
	v_cndmask_b32_e64 v169, v204, v51, s[22:23]
	v_cndmask_b32_e64 v87, v204, v46, s[24:25]
	v_fma_f32 v46, -v58, v110, v47
	v_fma_f32 v47, -v58, v111, v48
	v_max3_f32 v50, v50, v170, v169
	v_cndmask_b32_e64 v69, v204, v46, s[26:27]
	v_cndmask_b32_e64 v68, v204, v47, s[28:29]
	v_fma_f32 v47, -v58, v112, v49
	v_fma_f32 v38, -v58, v113, v38
	v_max3_f32 v46, v50, v87, v69
	v_cndmask_b32_e64 v67, v204, v47, s[30:31]
	v_cndmask_b32_e64 v66, v204, v38, s[34:35]
	v_fma_f32 v38, -v58, v114, v39
	v_max3_f32 v46, v46, v68, v67
	v_cndmask_b32_e64 v64, v204, v38, s[36:37]
	v_fma_f32 v38, -v58, v115, v40
; __device__ __forceinline__ void attn_unit(LAS unsigned char* lds, const bf16_t* PROJ, bf16_t* YCAT, const float* qg, const float* kg, const float* sinks, int unit, int tid, int wave, int lane) {
;     ...
;     float mx = -INFINITY;
; #pragma unroll
;     for (int rel = 0; rel < 10; ++rel)
; #pragma unroll
;         for (int i = 0; i < 4; ++i) {
;             const int kidx = 16 * (wp + rel) + 4 * fq + i, dist = qidx - kidx;
;             const bool valid = (dist >= 0) && (dist < 128) && (blk > 0 || kidx >= 128);
;             const float val = valid ? s[rel][i] - slope * (float)dist : -INFINITY;
;             s[rel][i] = val; mx = fmaxf(mx, val);
;         }
;     mx = fmaxf(mx, __shfl_xor(mx, 16)); mx = fmaxf(mx, __shfl_xor(mx, 32));
;     const float mm = fmaxf(mx, sink);
;     float ls = 0.f;
; #pragma unroll
;     for (int rel = 0; rel < 10; ++rel)
; #pragma unroll
;         for (int i = 0; i < 4; ++i) { const float p = __expf(s[rel][i] - mm); s[rel][i] = p; ls += p; }
;     ls += __shfl_xor(ls, 16); ls += __shfl_xor(ls, 32);
	v_fma_f32 v40, -v58, v116, v41
	v_fma_f32 v34, -v58, v117, v34
	v_max3_f32 v39, v46, v66, v64
	v_cndmask_b32_e64 v38, v204, v38, s[38:39]
	v_cndmask_b32_e64 v41, v204, v40, s[40:41]
	v_cndmask_b32_e64 v63, v204, v34, s[42:43]
	v_fma_f32 v34, -v58, v118, v35
	v_fma_f32 v35, -v58, v119, v36
	v_max3_f32 v39, v39, v38, v41
	v_cndmask_b32_e64 v62, v204, v34, s[44:45]
	v_cndmask_b32_e64 v61, v204, v35, s[46:47]
	v_fma_f32 v35, -v58, v120, v37
	v_fma_f32 v30, -v58, v121, v30
	v_max3_f32 v34, v39, v63, v62
	v_cndmask_b32_e64 v60, v204, v35, s[48:49]
	v_cndmask_b32_e64 v57, v204, v30, s[50:51]
	v_fma_f32 v30, -v58, v122, v31
	v_fma_f32 v31, -v58, v123, v32
	v_max3_f32 v34, v34, v61, v60
	v_cndmask_b32_e64 v56, v204, v30, s[52:53]
	v_cndmask_b32_e64 v55, v204, v31, s[54:55]
	v_fma_f32 v31, -v58, v124, v33
	v_fma_f32 v26, -v58, v125, v26
	v_max3_f32 v30, v34, v57, v56
	v_cndmask_b32_e64 v53, v204, v31, s[56:57]
	v_cndmask_b32_e64 v52, v204, v26, s[58:59]
	v_fma_f32 v26, -v58, v126, v27
	v_fma_f32 v27, -v58, v127, v28
	v_max3_f32 v30, v30, v55, v53
	v_cndmask_b32_e64 v51, v204, v26, s[60:61]
	v_cndmask_b32_e64 v50, v204, v27, s[62:63]
	v_fma_f32 v27, -v58, v128, v29
	v_fma_f32 v22, -v58, v129, v22
	v_fma_f32 v18, -v58, v133, v18
	v_max3_f32 v26, v30, v52, v51
	v_cndmask_b32_e64 v49, v204, v27, s[64:65]
	v_cndmask_b32_e64 v48, v204, v22, s[66:67]
	v_fma_f32 v22, -v58, v130, v23
	v_fma_f32 v23, -v58, v131, v24
	v_cndmask_b32_e64 v39, v204, v18, s[90:91]
	v_fma_f32 v18, -v58, v134, v19
	v_fma_f32 v19, -v58, v135, v20
	v_max3_f32 v26, v26, v50, v49
	v_cndmask_b32_e64 v47, v204, v22, s[68:69]
	v_cndmask_b32_e64 v46, v204, v23, s[70:71]
	v_fma_f32 v23, -v58, v132, v25
	v_cndmask_b32_e64 v36, v204, v19, s[94:95]
	v_fma_f32 v19, -v58, v136, v21
	v_max3_f32 v22, v26, v48, v47
	v_cndmask_b32_e64 v40, v204, v23, s[72:73]
	v_cndmask_b32_e64 v34, v204, v19, s[96:97]
	v_fma_f32 v19, -v58, v137, v42
	v_max3_f32 v22, v22, v46, v40
	v_cndmask_b32_e64 v37, v204, v18, s[92:93]
	v_cndmask_b32_e64 v33, v204, v19, s[4:5]
	v_fma_f32 v19, -v58, v138, v43
	v_max3_f32 v18, v22, v39, v37
	v_cndmask_b32_e64 v31, v204, v19, s[74:75]
	v_fma_f32 v19, -v58, v139, v44
	v_max3_f32 v18, v18, v36, v34
	v_cndmask_b32_e64 v30, v204, v19, s[6:7]
	v_fma_f32 v19, -v58, v140, v45
	v_max3_f32 v18, v18, v33, v31
	v_cndmask_b32_e64 v58, v204, v19, s[0:1]
	v_max3_f32 v18, v18, v30, v58
	ds_bpermute_b32 v19, v100, v18
	s_add_u32 s2, s2, 4
	s_addc_u32 s3, s3, 0
	s_cmp_lg_u32 s2, 16
	s_mov_b32 s78, s87
	s_waitcnt lgkmcnt(0)
	v_max_f32_e32 v19, v19, v19
	v_max_f32_e32 v18, v18, v19
	ds_bpermute_b32 v19, v101, v18
	s_waitcnt vmcnt(0) lgkmcnt(0)
	v_max3_f32 v65, v18, v19, v0
	v_sub_f32_e32 v18, v59, v65
	v_mul_f32_e32 v18, 0x3fb8aa3b, v18
	v_sub_f32_e32 v19, v54, v65
	v_exp_f32_e32 v18, v18
	v_mul_f32_e32 v19, 0x3fb8aa3b, v19
	v_exp_f32_e32 v19, v19
	v_sub_f32_e32 v38, v38, v65
	v_add_f32_e32 v20, 0, v18
	v_mul_f32_e32 v38, 0x3fb8aa3b, v38
	v_add_f32_e32 v21, v19, v20
	v_sub_f32_e32 v20, v174, v65
	v_mul_f32_e32 v20, 0x3fb8aa3b, v20
	v_exp_f32_e32 v20, v20
	v_sub_f32_e32 v41, v41, v65
	v_exp_f32_e32 v38, v38
	v_mul_f32_e32 v41, 0x3fb8aa3b, v41
	v_add_f32_e32 v22, v20, v21
	v_sub_f32_e32 v21, v173, v65
	v_mul_f32_e32 v21, 0x3fb8aa3b, v21
	v_exp_f32_e32 v21, v21
	v_exp_f32_e32 v41, v41
	v_sub_f32_e32 v56, v56, v65
	v_mul_f32_e32 v56, 0x3fb8aa3b, v56
	v_add_f32_e32 v23, v21, v22
	v_sub_f32_e32 v22, v172, v65
	v_mul_f32_e32 v22, 0x3fb8aa3b, v22
	v_exp_f32_e32 v22, v22
	v_sub_f32_e32 v55, v55, v65
	v_exp_f32_e32 v56, v56
	v_mul_f32_e32 v55, 0x3fb8aa3b, v55
	v_add_f32_e32 v24, v22, v23
	v_sub_f32_e32 v23, v171, v65
	v_mul_f32_e32 v23, 0x3fb8aa3b, v23
	v_exp_f32_e32 v23, v23
	v_sub_f32_e32 v53, v53, v65
	v_exp_f32_e32 v55, v55
	v_mul_f32_e32 v53, 0x3fb8aa3b, v53
	v_add_f32_e32 v25, v23, v24
	v_sub_f32_e32 v24, v170, v65
	v_mul_f32_e32 v24, 0x3fb8aa3b, v24
	v_exp_f32_e32 v24, v24
	v_sub_f32_e32 v52, v52, v65
	v_exp_f32_e32 v53, v53
	v_mul_f32_e32 v52, 0x3fb8aa3b, v52
	v_add_f32_e32 v26, v24, v25
	v_sub_f32_e32 v25, v169, v65
	v_mul_f32_e32 v25, 0x3fb8aa3b, v25
	v_exp_f32_e32 v25, v25
	v_sub_f32_e32 v51, v51, v65
	v_exp_f32_e32 v52, v52
	v_mul_f32_e32 v51, 0x3fb8aa3b, v51
	v_add_f32_e32 v27, v25, v26
	v_sub_f32_e32 v26, v87, v65
	v_mul_f32_e32 v26, 0x3fb8aa3b, v26
	v_exp_f32_e32 v26, v26
	v_sub_f32_e32 v50, v50, v65
	v_exp_f32_e32 v51, v51
	v_mul_f32_e32 v50, 0x3fb8aa3b, v50
	v_add_f32_e32 v28, v26, v27
	v_sub_f32_e32 v27, v69, v65
	v_mul_f32_e32 v27, 0x3fb8aa3b, v27
	v_exp_f32_e32 v27, v27
	v_sub_f32_e32 v49, v49, v65
	v_exp_f32_e32 v50, v50
	v_mul_f32_e32 v49, 0x3fb8aa3b, v49
	v_add_f32_e32 v29, v27, v28
	v_sub_f32_e32 v28, v68, v65
	v_mul_f32_e32 v28, 0x3fb8aa3b, v28
	v_exp_f32_e32 v28, v28
	v_sub_f32_e32 v48, v48, v65
	v_exp_f32_e32 v49, v49
	v_mul_f32_e32 v48, 0x3fb8aa3b, v48
	v_add_f32_e32 v32, v28, v29
	v_sub_f32_e32 v29, v67, v65
	v_mul_f32_e32 v29, 0x3fb8aa3b, v29
	v_exp_f32_e32 v29, v29
	v_sub_f32_e32 v47, v47, v65
	v_exp_f32_e32 v48, v48
	v_mul_f32_e32 v47, 0x3fb8aa3b, v47
	v_add_f32_e32 v35, v29, v32
	v_sub_f32_e32 v32, v66, v65
	v_mul_f32_e32 v32, 0x3fb8aa3b, v32
	v_exp_f32_e32 v32, v32
	v_sub_f32_e32 v46, v46, v65
	v_exp_f32_e32 v47, v47
	v_mul_f32_e32 v46, 0x3fb8aa3b, v46
	v_add_f32_e32 v42, v32, v35
	v_sub_f32_e32 v35, v64, v65
	v_mul_f32_e32 v35, 0x3fb8aa3b, v35
	v_exp_f32_e32 v35, v35
	v_sub_f32_e32 v40, v40, v65
	v_exp_f32_e32 v46, v46
	v_mul_f32_e32 v40, 0x3fb8aa3b, v40
	v_add_f32_e32 v42, v35, v42
	v_add_f32_e32 v42, v38, v42
	v_add_f32_e32 v43, v41, v42
	v_sub_f32_e32 v42, v63, v65
	v_mul_f32_e32 v42, 0x3fb8aa3b, v42
	v_exp_f32_e32 v42, v42
	v_sub_f32_e32 v39, v39, v65
	v_exp_f32_e32 v40, v40
; __device__ __forceinline__ unsigned cvt_pk_bf16(float lo, float hi) { unsigned r; asm volatile("v_cvt_pk_bf16_f32 %0, %1, %2" : "=v"(r) : "v"(lo), "v"(hi)); return r; }
; __device__ __forceinline__ u32x4 pack8(f32x4 a, f32x4 b) { u32x4 w; w.x = cvt_pk_bf16(a[0], a[1]); w.y = cvt_pk_bf16(a[2], a[3]); w.z = cvt_pk_bf16(b[0], b[1]); w.w = cvt_pk_bf16(b[2], b[3]); return w; }
; #define LAS __attribute__((address_space(3)))
; __device__ __forceinline__ void attn_unit(LAS unsigned char* lds, const bf16_t* PROJ, bf16_t* YCAT, const float* qg, const float* kg, const float* sinks, int unit, int tid, int wave, int lane) {
;     ...
;     ls += __shfl_xor(ls, 16); ls += __shfl_xor(ls, 32);
;     const float inv = 1.f / (ls + __expf(sink - mm));
;     bf16x8 pf[5];
; #pragma unroll
;     for (int g = 0; g < 5; ++g) pf[g] = as_bf8(pg8::pack8(s[2 * g], s[2 * g + 1]));
;     bf16_t* op = YCAT + (size_t)(t0 + qrow) * D + hq * 128 + 4 * fq;
; #pragma unroll
;     for (int db = 0; db < 8; ++db) {
;         f32x4 o = (f32x4){0.f, 0.f, 0.f, 0.f};
; #pragma unroll
;         for (int g = 0; g < 5; ++g) {
;             const bf16x8 vf = *(const LAS bf16x8*)(Vt + (16 * db + fr) * 264 + 32 * ((wp >> 1) + g) + 8 * fq);
;             o = __builtin_amdgcn_mfma_f32_16x16x32_bf16(vf, pf[g], o, 0, 0, 0);
;         }
;         u32x2 w; w.x = cvt_pk_bf16(o[0] * inv, o[1] * inv); w.y = cvt_pk_bf16(o[2] * inv, o[3] * inv);
;         *(u32x2*)(op + 16 * db) = w;
	v_mul_f32_e32 v39, 0x3fb8aa3b, v39
	v_add_f32_e32 v44, v42, v43
	v_sub_f32_e32 v43, v62, v65
	v_mul_f32_e32 v43, 0x3fb8aa3b, v43
	v_exp_f32_e32 v43, v43
	v_sub_f32_e32 v37, v37, v65
	v_exp_f32_e32 v39, v39
	v_mul_f32_e32 v37, 0x3fb8aa3b, v37
	v_add_f32_e32 v45, v43, v44
	v_sub_f32_e32 v44, v61, v65
	v_mul_f32_e32 v44, 0x3fb8aa3b, v44
	v_exp_f32_e32 v44, v44
	v_sub_f32_e32 v36, v36, v65
	v_exp_f32_e32 v37, v37
	v_mul_f32_e32 v36, 0x3fb8aa3b, v36
	v_add_f32_e32 v54, v44, v45
	v_sub_f32_e32 v45, v60, v65
	v_mul_f32_e32 v45, 0x3fb8aa3b, v45
	v_exp_f32_e32 v45, v45
	v_sub_f32_e32 v34, v34, v65
	v_exp_f32_e32 v36, v36
	v_mul_f32_e32 v34, 0x3fb8aa3b, v34
	v_add_f32_e32 v59, v45, v54
	v_sub_f32_e32 v54, v57, v65
	v_mul_f32_e32 v54, 0x3fb8aa3b, v54
	v_exp_f32_e32 v54, v54
	v_sub_f32_e32 v33, v33, v65
	v_mul_f32_e32 v33, 0x3fb8aa3b, v33
	v_sub_f32_e32 v31, v31, v65
	v_add_f32_e32 v57, v54, v59
	v_add_f32_e32 v57, v56, v57
	v_add_f32_e32 v57, v55, v57
	v_add_f32_e32 v57, v53, v57
	v_add_f32_e32 v57, v52, v57
	v_add_f32_e32 v57, v51, v57
	v_add_f32_e32 v57, v50, v57
	v_add_f32_e32 v57, v49, v57
	v_add_f32_e32 v57, v48, v57
	v_add_f32_e32 v57, v47, v57
	v_add_f32_e32 v57, v46, v57
	v_add_f32_e32 v57, v40, v57
	v_exp_f32_e32 v59, v34
	v_add_f32_e32 v57, v39, v57
	v_add_f32_e32 v57, v37, v57
	v_add_f32_e32 v57, v36, v57
	v_add_f32_e32 v34, v59, v57
	v_exp_f32_e32 v57, v33
	v_mul_f32_e32 v31, 0x3fb8aa3b, v31
	v_sub_f32_e32 v30, v30, v65
	v_exp_f32_e32 v60, v31
	v_mul_f32_e32 v30, 0x3fb8aa3b, v30
	v_exp_f32_e32 v61, v30
	v_add_f32_e32 v33, v57, v34
	v_add_f32_e32 v31, v60, v33
	v_sub_f32_e32 v0, v0, v65
	v_add_f32_e32 v30, v61, v31
	v_sub_f32_e32 v31, v58, v65
	v_mul_f32_e32 v31, 0x3fb8aa3b, v31
	v_exp_f32_e32 v58, v31
	v_mul_f32_e32 v0, 0x3fb8aa3b, v0
	v_exp_f32_e32 v0, v0
	v_cvt_pk_bf16_f32 v18, v18, v19
	v_add_f32_e32 v30, v58, v30
	ds_bpermute_b32 v31, v100, v30
	v_cvt_pk_bf16_f32 v19, v20, v21
	v_cvt_pk_bf16_f32 v20, v22, v23
	v_cvt_pk_bf16_f32 v21, v24, v25
	v_cvt_pk_bf16_f32 v22, v26, v27
	s_waitcnt lgkmcnt(0)
	v_add_f32_e32 v30, v30, v31
	ds_bpermute_b32 v31, v101, v30
	v_cvt_pk_bf16_f32 v23, v28, v29
	v_cvt_pk_bf16_f32 v24, v32, v35
	v_cvt_pk_bf16_f32 v25, v38, v41
	v_cvt_pk_bf16_f32 v26, v42, v43
	s_waitcnt lgkmcnt(0)
	v_add_f32_e32 v30, v30, v31
	v_add_f32_e32 v0, v0, v30
	v_div_scale_f32 v38, vcc, v0, v0, 1.0
	v_cvt_pk_bf16_f32 v27, v44, v45
	v_cvt_pk_bf16_f32 v28, v54, v56
	v_cvt_pk_bf16_f32 v29, v55, v53
	v_cvt_pk_bf16_f32 v30, v52, v51
	v_cvt_pk_bf16_f32 v31, v50, v49
	v_cvt_pk_bf16_f32 v32, v48, v47
	v_cvt_pk_bf16_f32 v33, v46, v40
	v_cvt_pk_bf16_f32 v34, v39, v37
	v_rcp_f32_e32 v39, v38
	v_cvt_pk_bf16_f32 v35, v36, v59
	v_cvt_pk_bf16_f32 v36, v57, v60
	v_cvt_pk_bf16_f32 v37, v61, v58
	s_nop 0
	v_fma_f32 v40, -v38, v39, 1.0
	v_fmac_f32_e32 v39, v40, v39
	v_div_scale_f32 v40, vcc, 1.0, v0, 1.0
	v_mul_f32_e32 v41, v40, v39
	v_fma_f32 v42, -v38, v41, v40
	v_fmac_f32_e32 v41, v42, v39
	v_fma_f32 v38, -v38, v41, v40
	v_div_fmas_f32 v38, v38, v39, v41
	v_div_fixup_f32 v0, v38, v0, 1.0
	ds_read_b128 v[176:179], v156
	ds_read_b128 v[180:183], v156 offset:64
	ds_read_b128 v[184:187], v156 offset:128
	ds_read_b128 v[188:191], v156 offset:192
	ds_read_b128 v[240:243], v156 offset:256
	ds_read_b128 v[244:247], v156 offset:8448
	ds_read_b128 v[248:251], v156 offset:8512
	ds_read_b128 v[170:173], v156 offset:8576
	ds_read_b128 v[54:57], v156 offset:8640
	ds_read_b128 v[42:45], v156 offset:8704
	s_mov_b64 vcc, 0x100
	s_waitcnt lgkmcnt(5)
	v_mfma_f32_16x16x32_bf16 v[46:49], v[176:179], v[18:21], 0
	v_mfma_f32_16x16x32_bf16 v[46:49], v[180:183], v[22:25], v[46:49]
	v_mfma_f32_16x16x32_bf16 v[46:49], v[184:187], v[26:29], v[46:49]
	v_mfma_f32_16x16x32_bf16 v[46:49], v[188:191], v[30:33], v[46:49]
	v_mfma_f32_16x16x32_bf16 v[46:49], v[240:243], v[34:37], v[46:49]
	ds_read_b128 v[176:179], v156 offset:16896
	ds_read_b128 v[180:183], v156 offset:16960
	ds_read_b128 v[184:187], v156 offset:17024
	ds_read_b128 v[188:191], v156 offset:17088
	ds_read_b128 v[240:243], v156 offset:17152
	s_waitcnt lgkmcnt(5)
	v_mfma_f32_16x16x32_bf16 v[50:53], v[244:247], v[18:21], 0
	v_mfma_f32_16x16x32_bf16 v[50:53], v[248:251], v[22:25], v[50:53]
	v_mfma_f32_16x16x32_bf16 v[50:53], v[170:173], v[26:29], v[50:53]
	v_mfma_f32_16x16x32_bf16 v[50:53], v[54:57], v[30:33], v[50:53]
	v_mfma_f32_16x16x32_bf16 v[50:53], v[42:45], v[34:37], v[50:53]
	ds_read_b128 v[244:247], v156 offset:25344
	ds_read_b128 v[248:251], v156 offset:25408
	ds_read_b128 v[170:173], v156 offset:25472
	ds_read_b128 v[54:57], v156 offset:25536
	ds_read_b128 v[42:45], v156 offset:25600
	v_mul_f32_e32 v38, v46, v0
	v_mul_f32_e32 v39, v47, v0
	v_cvt_pk_bf16_f32 v38, v38, v39
	v_mul_f32_e32 v39, v48, v0
	v_mul_f32_e32 v40, v49, v0
	v_cvt_pk_bf16_f32 v39, v39, v40
	global_store_dwordx2 v[90:91], v[38:39], off offset:-128
	s_waitcnt lgkmcnt(5)
; __device__ __forceinline__ unsigned cvt_pk_bf16(float lo, float hi) { unsigned r; asm volatile("v_cvt_pk_bf16_f32 %0, %1, %2" : "=v"(r) : "v"(lo), "v"(hi)); return r; }
; #define LAS __attribute__((address_space(3)))
; __device__ __forceinline__ void attn_unit(LAS unsigned char* lds, const bf16_t* PROJ, bf16_t* YCAT, const float* qg, const float* kg, const float* sinks, int unit, int tid, int wave, int lane) {
;     ...
;     for (int hq = 4 * kvh; hq < 4 * kvh + 4; ++hq) {
;     ...
; #pragma unroll
;     for (int db = 0; db < 8; ++db) {
;         f32x4 o = (f32x4){0.f, 0.f, 0.f, 0.f};
; #pragma unroll
;         for (int g = 0; g < 5; ++g) {
;             const bf16x8 vf = *(const LAS bf16x8*)(Vt + (16 * db + fr) * 264 + 32 * ((wp >> 1) + g) + 8 * fq);
;             o = __builtin_amdgcn_mfma_f32_16x16x32_bf16(vf, pf[g], o, 0, 0, 0);
;         }
;         u32x2 w; w.x = cvt_pk_bf16(o[0] * inv, o[1] * inv); w.y = cvt_pk_bf16(o[2] * inv, o[3] * inv);
;         *(u32x2*)(op + 16 * db) = w;
;     }
;     }
	v_mfma_f32_16x16x32_bf16 v[46:49], v[176:179], v[18:21], 0
	v_mfma_f32_16x16x32_bf16 v[46:49], v[180:183], v[22:25], v[46:49]
	v_mfma_f32_16x16x32_bf16 v[46:49], v[184:187], v[26:29], v[46:49]
	v_mfma_f32_16x16x32_bf16 v[46:49], v[188:191], v[30:33], v[46:49]
	v_mfma_f32_16x16x32_bf16 v[46:49], v[240:243], v[34:37], v[46:49]
	ds_read_b128 v[176:179], v156 offset:33792
	ds_read_b128 v[180:183], v156 offset:33856
	ds_read_b128 v[184:187], v156 offset:33920
	ds_read_b128 v[188:191], v156 offset:33984
	ds_read_b128 v[240:243], v156 offset:34048
	v_mul_f32_e32 v38, v50, v0
	v_mul_f32_e32 v39, v51, v0
	v_cvt_pk_bf16_f32 v38, v38, v39
	v_mul_f32_e32 v39, v52, v0
	v_mul_f32_e32 v40, v53, v0
	v_cvt_pk_bf16_f32 v39, v39, v40
	global_store_dwordx2 v[90:91], v[38:39], off offset:-96
	s_waitcnt lgkmcnt(5)
	v_mfma_f32_16x16x32_bf16 v[50:53], v[244:247], v[18:21], 0
	v_mfma_f32_16x16x32_bf16 v[50:53], v[248:251], v[22:25], v[50:53]
	v_mfma_f32_16x16x32_bf16 v[50:53], v[170:173], v[26:29], v[50:53]
	v_mfma_f32_16x16x32_bf16 v[50:53], v[54:57], v[30:33], v[50:53]
	v_mfma_f32_16x16x32_bf16 v[50:53], v[42:45], v[34:37], v[50:53]
	ds_read_b128 v[244:247], v156 offset:42240
	ds_read_b128 v[248:251], v156 offset:42304
	ds_read_b128 v[170:173], v156 offset:42368
	ds_read_b128 v[54:57], v156 offset:42432
	ds_read_b128 v[42:45], v156 offset:42496
	v_mul_f32_e32 v38, v46, v0
	v_mul_f32_e32 v39, v47, v0
	v_cvt_pk_bf16_f32 v38, v38, v39
	v_mul_f32_e32 v39, v48, v0
	v_mul_f32_e32 v40, v49, v0
	v_cvt_pk_bf16_f32 v39, v39, v40
	global_store_dwordx2 v[90:91], v[38:39], off offset:-64
	s_waitcnt lgkmcnt(5)
	v_mfma_f32_16x16x32_bf16 v[46:49], v[176:179], v[18:21], 0
	v_mfma_f32_16x16x32_bf16 v[46:49], v[180:183], v[22:25], v[46:49]
	v_mfma_f32_16x16x32_bf16 v[46:49], v[184:187], v[26:29], v[46:49]
	v_mfma_f32_16x16x32_bf16 v[46:49], v[188:191], v[30:33], v[46:49]
	v_mfma_f32_16x16x32_bf16 v[46:49], v[240:243], v[34:37], v[46:49]
	ds_read_b128 v[176:179], v156 offset:50688
	ds_read_b128 v[180:183], v156 offset:50752
	ds_read_b128 v[184:187], v156 offset:50816
	ds_read_b128 v[188:191], v156 offset:50880
	ds_read_b128 v[240:243], v156 offset:50944
	v_mul_f32_e32 v38, v50, v0
	v_mul_f32_e32 v39, v51, v0
	v_cvt_pk_bf16_f32 v38, v38, v39
	v_mul_f32_e32 v39, v52, v0
	v_mul_f32_e32 v40, v53, v0
	v_cvt_pk_bf16_f32 v39, v39, v40
	global_store_dwordx2 v[90:91], v[38:39], off offset:-32
	s_waitcnt lgkmcnt(5)
	v_mfma_f32_16x16x32_bf16 v[50:53], v[244:247], v[18:21], 0
	v_mfma_f32_16x16x32_bf16 v[50:53], v[248:251], v[22:25], v[50:53]
	v_mfma_f32_16x16x32_bf16 v[50:53], v[170:173], v[26:29], v[50:53]
	v_mfma_f32_16x16x32_bf16 v[50:53], v[54:57], v[30:33], v[50:53]
	v_mfma_f32_16x16x32_bf16 v[50:53], v[42:45], v[34:37], v[50:53]
	ds_read_b128 v[244:247], v168
	ds_read_b128 v[248:251], v168 offset:64
	ds_read_b128 v[170:173], v168 offset:128
	ds_read_b128 v[54:57], v168 offset:192
	ds_read_b128 v[42:45], v168 offset:256
	v_mul_f32_e32 v38, v46, v0
	v_mul_f32_e32 v39, v47, v0
	v_cvt_pk_bf16_f32 v38, v38, v39
	v_mul_f32_e32 v39, v48, v0
	v_mul_f32_e32 v40, v49, v0
	v_cvt_pk_bf16_f32 v39, v39, v40
	global_store_dwordx2 v[90:91], v[38:39], off
	s_waitcnt lgkmcnt(5)
	v_mfma_f32_16x16x32_bf16 v[46:49], v[176:179], v[18:21], 0
	v_mfma_f32_16x16x32_bf16 v[46:49], v[180:183], v[22:25], v[46:49]
	v_mfma_f32_16x16x32_bf16 v[46:49], v[184:187], v[26:29], v[46:49]
	v_mfma_f32_16x16x32_bf16 v[46:49], v[188:191], v[30:33], v[46:49]
	v_mfma_f32_16x16x32_bf16 v[46:49], v[240:243], v[34:37], v[46:49]
	s_nop 1
	v_mul_f32_e32 v38, v50, v0
	v_mul_f32_e32 v39, v51, v0
	v_cvt_pk_bf16_f32 v38, v38, v39
	v_mul_f32_e32 v39, v52, v0
	v_mul_f32_e32 v40, v53, v0
	v_cvt_pk_bf16_f32 v39, v39, v40
	global_store_dwordx2 v[90:91], v[38:39], off offset:32
	s_waitcnt lgkmcnt(0)
	v_mfma_f32_16x16x32_bf16 v[50:53], v[244:247], v[18:21], 0
	v_mfma_f32_16x16x32_bf16 v[50:53], v[248:251], v[22:25], v[50:53]
	v_mfma_f32_16x16x32_bf16 v[50:53], v[170:173], v[26:29], v[50:53]
	v_mfma_f32_16x16x32_bf16 v[50:53], v[54:57], v[30:33], v[50:53]
	v_mfma_f32_16x16x32_bf16 v[50:53], v[42:45], v[34:37], v[50:53]
	s_nop 1
	v_mul_f32_e32 v38, v46, v0
	v_mul_f32_e32 v39, v47, v0
	v_cvt_pk_bf16_f32 v38, v38, v39
	v_mul_f32_e32 v39, v48, v0
	v_mul_f32_e32 v40, v49, v0
	v_cvt_pk_bf16_f32 v39, v39, v40
	global_store_dwordx2 v[90:91], v[38:39], off offset:64
	v_mov_b64_e32 v[28:29], v[8:9]
	v_mov_b64_e32 v[26:27], v[6:7]
	v_mov_b64_e32 v[32:33], v[4:5]
	v_mov_b64_e32 v[30:31], v[2:3]
	v_mov_b64_e32 v[24:25], v[16:17]
	v_mov_b64_e32 v[22:23], v[14:15]
	v_mul_f32_e32 v38, v50, v0
	v_mul_f32_e32 v39, v51, v0
	v_cvt_pk_bf16_f32 v38, v38, v39
	v_mul_f32_e32 v39, v52, v0
	v_mul_f32_e32 v40, v53, v0
	v_cvt_pk_bf16_f32 v39, v39, v40
	global_store_dwordx2 v[90:91], v[38:39], off offset:96
	v_mov_b64_e32 v[20:21], v[12:13]
	v_lshl_add_u64 v[90:91], v[90:91], 0, vcc
	v_mov_b64_e32 v[18:19], v[10:11]
	s_cbranch_scc1 .LBB0_172
	v_readlane_b32 s2, v253, 54
	v_readlane_b32 s3, v253, 55
	s_add_i32 s83, s83, s2
	v_readlane_b32 s2, v253, 2
	s_add_i32 s82, s82, s2
	v_readlane_b32 s2, v253, 27
	v_readlane_b32 s24, v255, 45
	v_readlane_b32 s3, v253, 28
	v_readlane_b32 s25, v255, 46
	s_xor_b64 s[24:25], s[24:25], s[2:3]
	v_readlane_b32 s68, v254, 10
	s_mov_b32 s22, 0x800000
	s_cmpk_gt_i32 s83, 0xff
	v_readlane_b32 s23, v253, 59
	v_readlane_b32 s69, v254, 11
	s_barrier
	s_cbranch_scc0 .LBB0_157
